# attention loop back edge rotated: each wave half branches straight to its own loop top (inline latch, no shared latch / half re-test per step)
# speedup vs baseline: 1.0008x; 1.0008x over previous
; #define LAS __attribute__((address_space(3)))
; DI s16x4 vtr(const LAS char* p) { return __builtin_bit_cast(s16x4, __builtin_amdgcn_ds_read_tr16_b64_v4i16((LAS v4i16_t*)p)); }
; DI void attn_qk(const LAS char* kb, const bf16x8 (&qf)[4], bf16x8 (&pf)[4], float& l) {
;     f32x16 zero;
; #pragma unroll
;     for (int i = 0; i < 16; ++i) zero[i] = 0.f;
;     bf16x8 k0[4], k1[4];
; #pragma unroll
;     for (int s = 0; s < 4; ++s) k0[s] = *(const LAS bf16x8*)(kb + 32 * s);
; #pragma unroll
;     for (int s = 0; s < 4; ++s) k1[s] = *(const LAS bf16x8*)(kb + 32 * KRS + 32 * s);
;     f32x16 st0 = MFMA32(k0[0], qf[0], zero), st1 = MFMA32(k1[0], qf[0], zero);
; #pragma unroll
;     for (int s = 1; s < 4; ++s) { st0 = MFMA32(k0[s], qf[s], st0); st1 = MFMA32(k1[s], qf[s], st1); }
;     SGB(0x100, 8); SGB(0x008, 8);
;     float sum = 0.f;
; #pragma unroll
;     for (int i = 0; i < 16; ++i) { const float e = __builtin_amdgcn_exp2f(st0[i]); st0[i] = e; sum += e; }
;     pf[0] = pack8(st0, 0); pf[1] = pack8(st0, 1);
; #pragma unroll
;     for (int i = 0; i < 16; ++i) { const float e = __builtin_amdgcn_exp2f(st1[i]); st1[i] = e; sum += e; }
;     pf[2] = pack8(st1, 0); pf[3] = pack8(st1, 1);
;     l += sum;
; }
; DI void attn_pv(const LAS char* vb, const bf16x8 (&pf)[4], f32x16 (&O)[4]) {
;     s16x4 va[8], vc[8];
; #pragma unroll
;     for (int ks = 0; ks < 4; ++ks) { va[2 * ks] = vtr(vb + ks * 16 * VRS); va[2 * ks + 1] = vtr(vb + (ks * 16 + 8) * VRS); }
; #pragma unroll
;     for (int ks = 0; ks < 4; ++ks) { vc[2 * ks] = vtr(vb + ks * 16 * VRS + 64); vc[2 * ks + 1] = vtr(vb + (ks * 16 + 8) * VRS + 64); }
; DI void attn_unit(const Params& p, LAS unsigned char* ldsu, int kind, int b, int h, int u, float lam) {
;     ...
;         auto stage = [&](int t) { if (t >= ntl) t = ntl - 1; const int row0 = t == 0 ? ROW_M : b * SEQ + (t - 1) * 64;
;             dma_tile(lds + (t & 3) * SLOT_B, KB + (size_t)row0 * 512 + hc, VB + (size_t)row0 * 512 + hc, poff, wid); };
;         stage(0); stage(1); stage(2);
;         asm volatile("s_waitcnt vmcnt(10)" ::: "memory");
;         __syncthreads();
;         for (int t = 0; t < ntl; ++t) {
;             stage(t + 3);
;             const LAS char* sp = lds + (t & 3) * SLOT_B;
;             if (t <= my_last) { bf16x8 pf[4]; attn_qk(sp + kboff, qf, pf, l); attn_pv(sp + vboff, pf, O); }
;             BAR_LANDED();
.LattnA_top:
	s_add_i32 s22, s21, 3
	s_min_i32 s24, s22, s6
	s_lshl_b32 s22, s24, 6
	s_add_i32 s22, s17, s22
	s_and_b32 s24, s24, 3
	s_ashr_i32 s23, s22, 31
	s_mul_i32 s24, s24, 0x9400
	s_lshl_b64 s[22:23], s[22:23], 10
	s_add_u32 s25, s16, s22
	s_addc_u32 s26, s18, s23
	s_add_u32 s27, s19, s22
	s_addc_u32 s34, s20, s23
	s_cmp_gt_i32 s21, s29
	s_cbranch_scc1 .LattnA_skip
	s_and_b32 s35, s21, 3
	s_mul_i32 s35, s35, 0x9400
	v_add_u32_e32 v0, s35, v174
	v_add_u32_e32 v14, s35, v134
	ds_read_b128 v[2:5], v0
	ds_read_b128 v[6:9], v0 offset:32
	ds_read_b128 v[10:13], v0 offset:64
	ds_read_b128 v[136:139], v0 offset:96
	ds_read_b128 v[140:143], v0 offset:8704
	ds_read_b128 v[144:147], v0 offset:8736
	ds_read_b128 v[148:151], v0 offset:8768
	ds_read_b128 v[196:199], v0 offset:8800
	ds_read_b64_tr_b16 v[200:201], v14 offset:17408
	ds_read_b64_tr_b16 v[202:203], v14 offset:19968
	ds_read_b64_tr_b16 v[204:205], v14 offset:17472
	ds_read_b64_tr_b16 v[206:207], v14 offset:20032
	ds_read_b64_tr_b16 v[208:209], v14 offset:17536
	ds_read_b64_tr_b16 v[210:211], v14 offset:20096
	ds_read_b64_tr_b16 v[212:213], v14 offset:17600
	ds_read_b64_tr_b16 v[214:215], v14 offset:20160
	ds_read_b64_tr_b16 v[216:217], v14 offset:22528
	ds_read_b64_tr_b16 v[218:219], v14 offset:25088
	ds_read_b64_tr_b16 v[220:221], v14 offset:22592
	ds_read_b64_tr_b16 v[222:223], v14 offset:25152
	ds_read_b64_tr_b16 v[224:225], v14 offset:22656
	ds_read_b64_tr_b16 v[226:227], v14 offset:25216
	ds_read_b64_tr_b16 v[228:229], v14 offset:22720
	ds_read_b64_tr_b16 v[230:231], v14 offset:25280
	ds_read_b64_tr_b16 v[232:233], v14 offset:27648
	ds_read_b64_tr_b16 v[234:235], v14 offset:30208
	ds_read_b64_tr_b16 v[236:237], v14 offset:27712
	ds_read_b64_tr_b16 v[238:239], v14 offset:30272
	ds_read_b64_tr_b16 v[240:241], v14 offset:27776
	ds_read_b64_tr_b16 v[242:243], v14 offset:30336
	ds_read_b64_tr_b16 v[244:245], v14 offset:27840
	ds_read_b64_tr_b16 v[246:247], v14 offset:30400
	ds_read_b64_tr_b16 v[248:249], v14 offset:32768
	ds_read_b64_tr_b16 v[250:251], v14 offset:35328
	ds_read_b64_tr_b16 v[156:157], v14 offset:32832
	ds_read_b64_tr_b16 v[158:159], v14 offset:35392
	ds_read_b64_tr_b16 v[160:161], v14 offset:32896
	ds_read_b64_tr_b16 v[162:163], v14 offset:35456
	ds_read_b64_tr_b16 v[164:165], v14 offset:32960
	ds_read_b64_tr_b16 v[166:167], v14 offset:35520
	s_and_b64 s[22:23], s[0:1], exec
	s_cselect_b32 s23, s26, s34
	s_cselect_b32 s22, s25, s27
	s_add_i32 s35, s24, s7
	s_mov_b32 m0, s35
	s_nop 0
	global_load_lds_dwordx4 v132, s[22:23]
	s_add_i32 s35, s24, s10
	s_addk_i32 s35, 0x400
	s_mov_b32 m0, s35
	s_nop 0
	global_load_lds_dwordx4 v131, s[22:23]
	s_and_b64 s[22:23], exec, s[8:9]
	s_cselect_b32 s23, s26, s34
	s_cselect_b32 s22, s25, s27
	s_add_i32 s35, s24, s11
	s_addk_i32 s35, 0x800
	s_mov_b32 m0, s35
	s_nop 0
	global_load_lds_dwordx4 v130, s[22:23]
	s_add_i32 s35, s24, s12
	s_addk_i32 s35, 0xc00
	s_mov_b32 m0, s35
	s_nop 0
	global_load_lds_dwordx4 v129, s[22:23]
	s_add_i32 s35, s24, s13
	s_addk_i32 s35, 0x1000
	s_mov_b32 m0, s35
	s_nop 0
	global_load_lds_dwordx4 v133, s[22:23]
	s_waitcnt lgkmcnt(0)
	s_barrier
	v_mfma_f32_32x32x16_bf16 v[96:111], v[2:5], v[112:115], 0
	v_mfma_f32_32x32x16_bf16 v[96:111], v[6:9], v[116:119], v[96:111]
	v_mfma_f32_32x32x16_bf16 v[96:111], v[10:13], v[120:123], v[96:111]
	v_mfma_f32_32x32x16_bf16 v[96:111], v[136:139], v[124:127], v[96:111]
	s_nop 7
	s_nop 2
	v_mfma_f32_32x32x16_bf16 v[80:95], v[140:143], v[112:115], 0
	v_exp_f32_e32 v96, v96
	v_exp_f32_e32 v97, v97
	s_nop 0
	v_add_f32_e32 v15, v96, v97
	v_mfma_f32_32x32x16_bf16 v[80:95], v[144:147], v[116:119], v[80:95]
	v_exp_f32_e32 v98, v98
	v_exp_f32_e32 v99, v99
	v_cvt_pk_bf16_f32 v96, v96, v97
	v_add_f32_e32 v15, v98, v15
	v_mfma_f32_32x32x16_bf16 v[80:95], v[148:151], v[120:123], v[80:95]
	v_exp_f32_e32 v100, v100
	v_exp_f32_e32 v101, v101
	v_cvt_pk_bf16_f32 v97, v98, v99
	v_add_f32_e32 v15, v99, v15
	v_mfma_f32_32x32x16_bf16 v[80:95], v[196:199], v[124:127], v[80:95]
	v_exp_f32_e32 v102, v102
	v_exp_f32_e32 v103, v103
	v_cvt_pk_bf16_f32 v98, v100, v101
	v_cvt_pk_bf16_f32 v99, v102, v103
	s_nop 1
	v_mfma_f32_32x32x16_bf16 v[64:79], v[200:203], v[96:99], v[64:79]
	v_exp_f32_e32 v104, v104
	v_exp_f32_e32 v105, v105
	v_add_f32_e32 v15, v104, v15
	v_add_f32_e32 v15, v105, v15
	v_mfma_f32_32x32x16_bf16 v[48:63], v[204:207], v[96:99], v[48:63]
	v_exp_f32_e32 v106, v106
	v_exp_f32_e32 v107, v107
	v_cvt_pk_bf16_f32 v104, v104, v105
	v_add_f32_e32 v15, v106, v15
	v_mfma_f32_32x32x16_bf16 v[32:47], v[208:211], v[96:99], v[32:47]
	v_exp_f32_e32 v108, v108
	v_exp_f32_e32 v109, v109
	v_cvt_pk_bf16_f32 v105, v106, v107
	v_add_f32_e32 v15, v107, v15
	v_mfma_f32_32x32x16_bf16 v[16:31], v[212:215], v[96:99], v[16:31]
	v_exp_f32_e32 v110, v110
	v_exp_f32_e32 v111, v111
	v_cvt_pk_bf16_f32 v106, v108, v109
	v_cvt_pk_bf16_f32 v107, v110, v111
	s_nop 1
	v_mfma_f32_32x32x16_bf16 v[64:79], v[216:219], v[104:107], v[64:79]
	v_exp_f32_e32 v80, v80
	v_exp_f32_e32 v81, v81
	v_add_f32_e32 v15, v80, v15
	v_add_f32_e32 v15, v81, v15
	v_mfma_f32_32x32x16_bf16 v[48:63], v[220:223], v[104:107], v[48:63]
	v_exp_f32_e32 v82, v82
	v_exp_f32_e32 v83, v83
	v_cvt_pk_bf16_f32 v80, v80, v81
	v_add_f32_e32 v15, v82, v15
	v_mfma_f32_32x32x16_bf16 v[32:47], v[224:227], v[104:107], v[32:47]
	v_exp_f32_e32 v84, v84
	v_exp_f32_e32 v85, v85
	v_cvt_pk_bf16_f32 v81, v82, v83
	v_add_f32_e32 v15, v83, v15
	v_mfma_f32_32x32x16_bf16 v[16:31], v[228:231], v[104:107], v[16:31]
	v_exp_f32_e32 v86, v86
	v_exp_f32_e32 v87, v87
	v_cvt_pk_bf16_f32 v82, v84, v85
	v_cvt_pk_bf16_f32 v83, v86, v87
	s_nop 1
	v_mfma_f32_32x32x16_bf16 v[64:79], v[232:235], v[80:83], v[64:79]
; #define LAS __attribute__((address_space(3)))
; DI s16x4 vtr(const LAS char* p) { return __builtin_bit_cast(s16x4, __builtin_amdgcn_ds_read_tr16_b64_v4i16((LAS v4i16_t*)p)); }
; DI bf16x8 cat4(s16x4 lo, s16x4 hi) { return __builtin_shufflevector(lo, hi, 0, 1, 2, 3, 4, 5, 6, 7); }
; #define MFMA32(a, b, c) __builtin_amdgcn_mfma_f32_32x32x16_bf16((a), (b), (c), 0, 0, 0)
; #define SGB(mask, n) __builtin_amdgcn_sched_group_barrier((mask), (n), 0)
; #define BAR_LANDED() asm volatile("s_waitcnt vmcnt(10)\n\ts_barrier" ::: "memory")
; DI void attn_pv(const LAS char* vb, const bf16x8 (&pf)[4], f32x16 (&O)[4]) {
;     ...
; #pragma unroll
;     for (int ks = 0; ks < 4; ++ks) { va[2 * ks] = vtr(vb + ks * 16 * VRS); va[2 * ks + 1] = vtr(vb + (ks * 16 + 8) * VRS); }
; #pragma unroll
;     for (int ks = 0; ks < 4; ++ks) { vc[2 * ks] = vtr(vb + ks * 16 * VRS + 64); vc[2 * ks + 1] = vtr(vb + (ks * 16 + 8) * VRS + 64); }
; #pragma unroll
;     for (int ks = 0; ks < 4; ++ks) O[0] = MFMA32(cat4(va[2 * ks], va[2 * ks + 1]), pf[ks], O[0]);
; #pragma unroll
;     for (int ks = 0; ks < 4; ++ks) { va[2 * ks] = vtr(vb + ks * 16 * VRS + 128); va[2 * ks + 1] = vtr(vb + (ks * 16 + 8) * VRS + 128); }
;     SGB(0x100, 16); SGB(0x008, 4); SGB(0x100, 8);
; #pragma unroll
;     for (int ks = 0; ks < 4; ++ks) O[1] = MFMA32(cat4(vc[2 * ks], vc[2 * ks + 1]), pf[ks], O[1]);
; #pragma unroll
;     for (int ks = 0; ks < 4; ++ks) { vc[2 * ks] = vtr(vb + ks * 16 * VRS + 192); vc[2 * ks + 1] = vtr(vb + (ks * 16 + 8) * VRS + 192); }
;     SGB(0x008, 4); SGB(0x100, 8);
; #pragma unroll
;     for (int ks = 0; ks < 4; ++ks) O[2] = MFMA32(cat4(va[2 * ks], va[2 * ks + 1]), pf[ks], O[2]);
;     SGB(0x008, 4);
; #pragma unroll
;     for (int ks = 0; ks < 4; ++ks) O[3] = MFMA32(cat4(vc[2 * ks], vc[2 * ks + 1]), pf[ks], O[3]);
;     SGB(0x008, 4);
; }
; DI void attn_unit(const Params& p, LAS unsigned char* ldsu, int kind, int b, int h, int u, float lam) {
;     ...
;         for (int t = 0; t < ntl; ++t) {
;             stage(t + 3);
;             const LAS char* sp = lds + (t & 3) * SLOT_B;
;             if (t <= my_last) { bf16x8 pf[4]; attn_qk(sp + kboff, qf, pf, l); attn_pv(sp + vboff, pf, O); }
;             BAR_LANDED();
	v_exp_f32_e32 v88, v88
	v_exp_f32_e32 v89, v89
	v_add_f32_e32 v15, v88, v15
	v_add_f32_e32 v15, v89, v15
	v_mfma_f32_32x32x16_bf16 v[48:63], v[236:239], v[80:83], v[48:63]
	v_exp_f32_e32 v90, v90
	v_exp_f32_e32 v91, v91
	v_cvt_pk_bf16_f32 v88, v88, v89
	v_add_f32_e32 v15, v90, v15
	v_mfma_f32_32x32x16_bf16 v[32:47], v[240:243], v[80:83], v[32:47]
	v_exp_f32_e32 v92, v92
	v_exp_f32_e32 v93, v93
	v_cvt_pk_bf16_f32 v89, v90, v91
	v_add_f32_e32 v15, v91, v15
	v_mfma_f32_32x32x16_bf16 v[16:31], v[244:247], v[80:83], v[16:31]
	v_exp_f32_e32 v94, v94
	v_exp_f32_e32 v95, v95
	v_cvt_pk_bf16_f32 v90, v92, v93
	v_cvt_pk_bf16_f32 v91, v94, v95
	s_nop 1
	v_mfma_f32_32x32x16_bf16 v[64:79], v[248:251], v[88:91], v[64:79]
	v_add_f32_e32 v15, v100, v15
	v_add_f32_e32 v15, v101, v15
	v_add_f32_e32 v15, v102, v15
	v_add_f32_e32 v15, v103, v15
	v_mfma_f32_32x32x16_bf16 v[48:63], v[156:159], v[88:91], v[48:63]
	v_add_f32_e32 v15, v108, v15
	v_add_f32_e32 v15, v109, v15
	v_add_f32_e32 v15, v110, v15
	v_add_f32_e32 v15, v111, v15
	v_mfma_f32_32x32x16_bf16 v[32:47], v[160:163], v[88:91], v[32:47]
	v_add_f32_e32 v15, v84, v15
	v_add_f32_e32 v15, v85, v15
	v_add_f32_e32 v15, v86, v15
	v_add_f32_e32 v15, v87, v15
	v_mfma_f32_32x32x16_bf16 v[16:31], v[164:167], v[88:91], v[16:31]
	v_add_f32_e32 v15, v92, v15
	v_add_f32_e32 v15, v93, v15
	v_add_f32_e32 v15, v94, v15
	v_add_f32_e32 v15, v95, v15
	v_add_f32_e32 v175, v175, v15
	s_waitcnt vmcnt(10)
	s_barrier
	s_add_i32 s21, s21, 1
	s_cmp_eq_u32 s31, s21
	s_cbranch_scc0 .LattnA_top
	s_branch .Lattn_exit
.LattnA_skip:
	s_and_b64 s[22:23], s[0:1], exec
	s_cselect_b32 s23, s26, s34
	s_cselect_b32 s22, s25, s27
	s_add_i32 s35, s24, s7
	s_mov_b32 m0, s35
	s_nop 0
	global_load_lds_dwordx4 v132, s[22:23]
	s_add_i32 s35, s24, s10
	s_addk_i32 s35, 0x400
	s_mov_b32 m0, s35
	s_nop 0
	global_load_lds_dwordx4 v131, s[22:23]
	s_and_b64 s[22:23], exec, s[8:9]
	s_cselect_b32 s23, s26, s34
	s_cselect_b32 s22, s25, s27
	s_add_i32 s35, s24, s11
	s_addk_i32 s35, 0x800
	s_mov_b32 m0, s35
	s_nop 0
	global_load_lds_dwordx4 v130, s[22:23]
	s_add_i32 s35, s24, s12
	s_addk_i32 s35, 0xc00
	s_mov_b32 m0, s35
	s_nop 0
	global_load_lds_dwordx4 v129, s[22:23]
	s_add_i32 s35, s24, s13
	s_addk_i32 s35, 0x1000
	s_mov_b32 m0, s35
	s_nop 0
	global_load_lds_dwordx4 v133, s[22:23]
	s_barrier
	s_waitcnt vmcnt(10)
	s_barrier
	s_add_i32 s21, s21, 1
	s_cmp_eq_u32 s31, s21
	s_cbranch_scc0 .LattnA_top
	s_branch .Lattn_exit
.LattnB:
	s_add_i32 s22, s21, 3
	s_min_i32 s24, s22, s6
	s_lshl_b32 s22, s24, 6
	s_add_i32 s22, s17, s22
	s_and_b32 s24, s24, 3
	s_ashr_i32 s23, s22, 31
	s_mul_i32 s24, s24, 0x9400
	s_lshl_b64 s[22:23], s[22:23], 10
	s_add_u32 s25, s16, s22
	s_addc_u32 s26, s18, s23
	s_add_u32 s27, s19, s22
	s_addc_u32 s34, s20, s23
	s_cmp_gt_i32 s21, s29
	s_cbranch_scc1 .LattnB_skip
	s_and_b32 s35, s21, 3
	s_mul_i32 s35, s35, 0x9400
	v_add_u32_e32 v0, s35, v174
	v_add_u32_e32 v14, s35, v134
	ds_read_b128 v[2:5], v0
	ds_read_b128 v[6:9], v0 offset:32
	ds_read_b128 v[10:13], v0 offset:64
	ds_read_b128 v[136:139], v0 offset:96
	ds_read_b128 v[140:143], v0 offset:8704
	ds_read_b128 v[144:147], v0 offset:8736
	ds_read_b128 v[148:151], v0 offset:8768
	ds_read_b128 v[196:199], v0 offset:8800
	ds_read_b64_tr_b16 v[200:201], v14 offset:17408
	ds_read_b64_tr_b16 v[202:203], v14 offset:19968
	ds_read_b64_tr_b16 v[204:205], v14 offset:17472
	ds_read_b64_tr_b16 v[206:207], v14 offset:20032
	ds_read_b64_tr_b16 v[208:209], v14 offset:17536
	ds_read_b64_tr_b16 v[210:211], v14 offset:20096
	ds_read_b64_tr_b16 v[212:213], v14 offset:17600
	ds_read_b64_tr_b16 v[214:215], v14 offset:20160
	ds_read_b64_tr_b16 v[216:217], v14 offset:22528
	ds_read_b64_tr_b16 v[218:219], v14 offset:25088
	ds_read_b64_tr_b16 v[220:221], v14 offset:22592
	ds_read_b64_tr_b16 v[222:223], v14 offset:25152
	ds_read_b64_tr_b16 v[224:225], v14 offset:22656
	ds_read_b64_tr_b16 v[226:227], v14 offset:25216
	ds_read_b64_tr_b16 v[228:229], v14 offset:22720
	ds_read_b64_tr_b16 v[230:231], v14 offset:25280
	ds_read_b64_tr_b16 v[232:233], v14 offset:27648
	ds_read_b64_tr_b16 v[234:235], v14 offset:30208
	ds_read_b64_tr_b16 v[236:237], v14 offset:27712
	ds_read_b64_tr_b16 v[238:239], v14 offset:30272
	ds_read_b64_tr_b16 v[240:241], v14 offset:27776
	ds_read_b64_tr_b16 v[242:243], v14 offset:30336
	ds_read_b64_tr_b16 v[244:245], v14 offset:27840
	ds_read_b64_tr_b16 v[246:247], v14 offset:30400
	ds_read_b64_tr_b16 v[248:249], v14 offset:32768
	ds_read_b64_tr_b16 v[250:251], v14 offset:35328
	ds_read_b64_tr_b16 v[156:157], v14 offset:32832
	ds_read_b64_tr_b16 v[158:159], v14 offset:35392
	ds_read_b64_tr_b16 v[160:161], v14 offset:32896
	ds_read_b64_tr_b16 v[162:163], v14 offset:35456
	ds_read_b64_tr_b16 v[164:165], v14 offset:32960
	ds_read_b64_tr_b16 v[166:167], v14 offset:35520
	s_and_b64 s[22:23], s[0:1], exec
	s_cselect_b32 s23, s26, s34
	s_cselect_b32 s22, s25, s27
	s_add_i32 s35, s24, s7
	s_mov_b32 m0, s35
	s_nop 0
	global_load_lds_dwordx4 v132, s[22:23]
	s_add_i32 s35, s24, s10
	s_addk_i32 s35, 0x400
	s_mov_b32 m0, s35
	s_nop 0
	global_load_lds_dwordx4 v131, s[22:23]
	s_and_b64 s[22:23], exec, s[8:9]
	s_cselect_b32 s23, s26, s34
	s_cselect_b32 s22, s25, s27
	s_add_i32 s35, s24, s11
	s_addk_i32 s35, 0x800
	s_mov_b32 m0, s35
	s_nop 0
	global_load_lds_dwordx4 v130, s[22:23]
	s_add_i32 s35, s24, s12
	s_addk_i32 s35, 0xc00
	s_mov_b32 m0, s35
	s_nop 0
	global_load_lds_dwordx4 v129, s[22:23]
	s_add_i32 s35, s24, s13
	s_addk_i32 s35, 0x1000
	s_mov_b32 m0, s35
	s_nop 0
	global_load_lds_dwordx4 v133, s[22:23]
	s_waitcnt vmcnt(10)
	s_waitcnt lgkmcnt(0)
	s_barrier
; DI void attn_qk(const LAS char* kb, const bf16x8 (&qf)[4], bf16x8 (&pf)[4], float& l) {
;     f32x16 zero;
; #pragma unroll
;     for (int i = 0; i < 16; ++i) zero[i] = 0.f;
;     bf16x8 k0[4], k1[4];
; #pragma unroll
;     for (int s = 0; s < 4; ++s) k0[s] = *(const LAS bf16x8*)(kb + 32 * s);
; #pragma unroll
;     for (int s = 0; s < 4; ++s) k1[s] = *(const LAS bf16x8*)(kb + 32 * KRS + 32 * s);
;     f32x16 st0 = MFMA32(k0[0], qf[0], zero), st1 = MFMA32(k1[0], qf[0], zero);
; #pragma unroll
;     for (int s = 1; s < 4; ++s) { st0 = MFMA32(k0[s], qf[s], st0); st1 = MFMA32(k1[s], qf[s], st1); }
;     SGB(0x100, 8); SGB(0x008, 8);
;     float sum = 0.f;
; #pragma unroll
;     for (int i = 0; i < 16; ++i) { const float e = __builtin_amdgcn_exp2f(st0[i]); st0[i] = e; sum += e; }
;     pf[0] = pack8(st0, 0); pf[1] = pack8(st0, 1);
; #pragma unroll
;     for (int i = 0; i < 16; ++i) { const float e = __builtin_amdgcn_exp2f(st1[i]); st1[i] = e; sum += e; }
;     pf[2] = pack8(st1, 0); pf[3] = pack8(st1, 1);
;     l += sum;
; }
; DI void attn_pv(const LAS char* vb, const bf16x8 (&pf)[4], f32x16 (&O)[4]) {
;     s16x4 va[8], vc[8];
; #pragma unroll
;     for (int ks = 0; ks < 4; ++ks) { va[2 * ks] = vtr(vb + ks * 16 * VRS); va[2 * ks + 1] = vtr(vb + (ks * 16 + 8) * VRS); }
; #pragma unroll
;     for (int ks = 0; ks < 4; ++ks) { vc[2 * ks] = vtr(vb + ks * 16 * VRS + 64); vc[2 * ks + 1] = vtr(vb + (ks * 16 + 8) * VRS + 64); }
; #pragma unroll
;     for (int ks = 0; ks < 4; ++ks) O[0] = MFMA32(cat4(va[2 * ks], va[2 * ks + 1]), pf[ks], O[0]);
; #pragma unroll
;     for (int ks = 0; ks < 4; ++ks) { va[2 * ks] = vtr(vb + ks * 16 * VRS + 128); va[2 * ks + 1] = vtr(vb + (ks * 16 + 8) * VRS + 128); }
;     SGB(0x100, 16); SGB(0x008, 4); SGB(0x100, 8);
; #pragma unroll
;     for (int ks = 0; ks < 4; ++ks) O[1] = MFMA32(cat4(vc[2 * ks], vc[2 * ks + 1]), pf[ks], O[1]);
; #pragma unroll
;     for (int ks = 0; ks < 4; ++ks) { vc[2 * ks] = vtr(vb + ks * 16 * VRS + 192); vc[2 * ks + 1] = vtr(vb + (ks * 16 + 8) * VRS + 192); }
;     SGB(0x008, 4); SGB(0x100, 8);
; #pragma unroll
;     for (int ks = 0; ks < 4; ++ks) O[2] = MFMA32(cat4(va[2 * ks], va[2 * ks + 1]), pf[ks], O[2]);
;     SGB(0x008, 4);
; #pragma unroll
;     for (int ks = 0; ks < 4; ++ks) O[3] = MFMA32(cat4(vc[2 * ks], vc[2 * ks + 1]), pf[ks], O[3]);
;     SGB(0x008, 4);
; }
	v_mfma_f32_32x32x16_bf16 v[96:111], v[2:5], v[112:115], 0
	v_mfma_f32_32x32x16_bf16 v[96:111], v[6:9], v[116:119], v[96:111]
	v_mfma_f32_32x32x16_bf16 v[96:111], v[10:13], v[120:123], v[96:111]
	v_mfma_f32_32x32x16_bf16 v[96:111], v[136:139], v[124:127], v[96:111]
	s_nop 7
	s_nop 2
	v_mfma_f32_32x32x16_bf16 v[80:95], v[140:143], v[112:115], 0
	v_exp_f32_e32 v96, v96
	v_exp_f32_e32 v97, v97
	s_nop 0
	v_add_f32_e32 v15, v96, v97
	v_mfma_f32_32x32x16_bf16 v[80:95], v[144:147], v[116:119], v[80:95]
	v_exp_f32_e32 v98, v98
	v_exp_f32_e32 v99, v99
	v_cvt_pk_bf16_f32 v96, v96, v97
	v_add_f32_e32 v15, v98, v15
	v_mfma_f32_32x32x16_bf16 v[80:95], v[148:151], v[120:123], v[80:95]
	v_exp_f32_e32 v100, v100
	v_exp_f32_e32 v101, v101
	v_cvt_pk_bf16_f32 v97, v98, v99
	v_add_f32_e32 v15, v99, v15
	v_mfma_f32_32x32x16_bf16 v[80:95], v[196:199], v[124:127], v[80:95]
	v_exp_f32_e32 v102, v102
	v_exp_f32_e32 v103, v103
	v_cvt_pk_bf16_f32 v98, v100, v101
	v_cvt_pk_bf16_f32 v99, v102, v103
	s_nop 1
	v_mfma_f32_32x32x16_bf16 v[64:79], v[200:203], v[96:99], v[64:79]
	v_exp_f32_e32 v104, v104
	v_exp_f32_e32 v105, v105
	v_add_f32_e32 v15, v104, v15
	v_add_f32_e32 v15, v105, v15
	v_mfma_f32_32x32x16_bf16 v[48:63], v[204:207], v[96:99], v[48:63]
	v_exp_f32_e32 v106, v106
	v_exp_f32_e32 v107, v107
	v_cvt_pk_bf16_f32 v104, v104, v105
	v_add_f32_e32 v15, v106, v15
	v_mfma_f32_32x32x16_bf16 v[32:47], v[208:211], v[96:99], v[32:47]
	v_exp_f32_e32 v108, v108
	v_exp_f32_e32 v109, v109
	v_cvt_pk_bf16_f32 v105, v106, v107
	v_add_f32_e32 v15, v107, v15
	v_mfma_f32_32x32x16_bf16 v[16:31], v[212:215], v[96:99], v[16:31]
	v_exp_f32_e32 v110, v110
	v_exp_f32_e32 v111, v111
	v_cvt_pk_bf16_f32 v106, v108, v109
	v_cvt_pk_bf16_f32 v107, v110, v111
	s_nop 1
	v_mfma_f32_32x32x16_bf16 v[64:79], v[216:219], v[104:107], v[64:79]
	v_exp_f32_e32 v80, v80
	v_exp_f32_e32 v81, v81
	v_add_f32_e32 v15, v80, v15
	v_add_f32_e32 v15, v81, v15
	v_mfma_f32_32x32x16_bf16 v[48:63], v[220:223], v[104:107], v[48:63]
	v_exp_f32_e32 v82, v82
	v_exp_f32_e32 v83, v83
	v_cvt_pk_bf16_f32 v80, v80, v81
	v_add_f32_e32 v15, v82, v15
	v_mfma_f32_32x32x16_bf16 v[32:47], v[224:227], v[104:107], v[32:47]
	v_exp_f32_e32 v84, v84
	v_exp_f32_e32 v85, v85
	v_cvt_pk_bf16_f32 v81, v82, v83
	v_add_f32_e32 v15, v83, v15
	v_mfma_f32_32x32x16_bf16 v[16:31], v[228:231], v[104:107], v[16:31]
	v_exp_f32_e32 v86, v86
	v_exp_f32_e32 v87, v87
	v_cvt_pk_bf16_f32 v82, v84, v85
	v_cvt_pk_bf16_f32 v83, v86, v87
	s_nop 1
	v_mfma_f32_32x32x16_bf16 v[64:79], v[232:235], v[80:83], v[64:79]
	v_exp_f32_e32 v88, v88
	v_exp_f32_e32 v89, v89
	v_add_f32_e32 v15, v88, v15
	v_add_f32_e32 v15, v89, v15
	v_mfma_f32_32x32x16_bf16 v[48:63], v[236:239], v[80:83], v[48:63]
	v_exp_f32_e32 v90, v90
	v_exp_f32_e32 v91, v91
	v_cvt_pk_bf16_f32 v88, v88, v89
	v_add_f32_e32 v15, v90, v15
	v_mfma_f32_32x32x16_bf16 v[32:47], v[240:243], v[80:83], v[32:47]
	v_exp_f32_e32 v92, v92
	v_exp_f32_e32 v93, v93
	v_cvt_pk_bf16_f32 v89, v90, v91
	v_add_f32_e32 v15, v91, v15
	v_mfma_f32_32x32x16_bf16 v[16:31], v[244:247], v[80:83], v[16:31]
	v_exp_f32_e32 v94, v94
	v_exp_f32_e32 v95, v95
	v_cvt_pk_bf16_f32 v90, v92, v93
	v_cvt_pk_bf16_f32 v91, v94, v95
	s_nop 1
	v_mfma_f32_32x32x16_bf16 v[64:79], v[248:251], v[88:91], v[64:79]
	v_add_f32_e32 v15, v100, v15
	v_add_f32_e32 v15, v101, v15
	v_add_f32_e32 v15, v102, v15
	v_add_f32_e32 v15, v103, v15
	v_mfma_f32_32x32x16_bf16 v[48:63], v[156:159], v[88:91], v[48:63]
	v_add_f32_e32 v15, v108, v15
	v_add_f32_e32 v15, v109, v15
	v_add_f32_e32 v15, v110, v15
	v_add_f32_e32 v15, v111, v15
	v_mfma_f32_32x32x16_bf16 v[32:47], v[160:163], v[88:91], v[32:47]
	v_add_f32_e32 v15, v84, v15
	v_add_f32_e32 v15, v85, v15
	v_add_f32_e32 v15, v86, v15
	v_add_f32_e32 v15, v87, v15
	v_mfma_f32_32x32x16_bf16 v[16:31], v[164:167], v[88:91], v[16:31]
	v_add_f32_e32 v15, v92, v15
	v_add_f32_e32 v15, v93, v15
	v_add_f32_e32 v15, v94, v15
	v_add_f32_e32 v15, v95, v15
	v_add_f32_e32 v175, v175, v15
	s_barrier
	s_add_i32 s21, s21, 1
	s_cmp_eq_u32 s31, s21
	s_cbranch_scc0 .LattnB
	s_branch .Lattn_exit
.LattnB_skip:
	s_and_b64 s[22:23], s[0:1], exec
	s_cselect_b32 s23, s26, s34
	s_cselect_b32 s22, s25, s27
	s_add_i32 s35, s24, s7
	s_mov_b32 m0, s35
	s_nop 0
	global_load_lds_dwordx4 v132, s[22:23]
	s_add_i32 s35, s24, s10
	s_addk_i32 s35, 0x400
	s_mov_b32 m0, s35
	s_nop 0
	global_load_lds_dwordx4 v131, s[22:23]
	s_and_b64 s[22:23], exec, s[8:9]
	s_cselect_b32 s23, s26, s34
	s_cselect_b32 s22, s25, s27
	s_add_i32 s35, s24, s11
	s_addk_i32 s35, 0x800
	s_mov_b32 m0, s35
	s_nop 0
	global_load_lds_dwordx4 v130, s[22:23]
	s_add_i32 s35, s24, s12
	s_addk_i32 s35, 0xc00
	s_mov_b32 m0, s35
	s_nop 0
	global_load_lds_dwordx4 v129, s[22:23]
	s_add_i32 s35, s24, s13
	s_addk_i32 s35, 0x1000
	s_mov_b32 m0, s35
	s_nop 0
	global_load_lds_dwordx4 v133, s[22:23]
	s_waitcnt vmcnt(10)
	s_barrier
	s_barrier
	s_add_i32 s21, s21, 1
	s_cmp_eq_u32 s31, s21
	s_cbranch_scc0 .LattnB
	s_branch .Lattn_exit
